# v25 with all 288 per-MFMA-block s_setprio toggles removed (no priority changes at all)
# baseline (speedup 1.0000x reference)
; #define PG8_STAGE(bufoff, gbase, voff) do { _Pragma("unroll") for (int _i = 0; _i < 2; ++_i) \
;         __builtin_amdgcn_global_load_lds((const unsigned*)((const char*)(gbase) + (voff)[_i]), (PG8_LAS unsigned*)(lds + (bufoff) + ldsw + _i * 8192), 16, 0, 0); } while (0)
; #define PG8_LDA(dst, b, h) do { _Pragma("unroll") for (int m = 0; m < 4; ++m) _Pragma("unroll") for (int k = 0; k < 2; ++k) dst[m][k] = *(const PG8_LAS bf16x8*)(lds + PG8_SA(b, h) + aoff + m * 2048 + k * 1024); } while (0)
; #define PG8_MMA(ai, bj, At, Bt) do { __builtin_amdgcn_s_setprio(1); _Pragma("unroll") for (int m = 0; m < 4; ++m) _Pragma("unroll") for (int n = 0; n < 2; ++n) _Pragma("unroll") for (int k = 0; k < 2; ++k) \
;         acc[ai][bj][m][n] = mma16<F16>(Bt[n][k], At[m][k], acc[ai][bj][m][n]); __builtin_amdgcn_s_setprio(0); } while (0)
; #define PG8_WAIT_V(n) asm volatile("s_waitcnt vmcnt(" #n ")" ::: "memory")
; #define PG8_WAIT_L(n) asm volatile("s_waitcnt lgkmcnt(" #n ")" ::: "memory")
; #define PG8_BAR __builtin_amdgcn_s_barrier()
; #define PG8_SCHED __builtin_amdgcn_sched_barrier(0)
; template <class Epi, class Sched, bool ALIGN_EPI = false, bool SP2 = false, bool F16 = false, bool TOKPERM = false>
; __device__ __forceinline__ void gemm_phase(PG8_LAS unsigned char* lds, const Gemm g, const Sched& S, const Epi& E, int wv) {
;     ...
;             PG8_WAIT_V(8); PG8_WAIT_L(0); PG8_BAR; PG8_MMA(0, 0, At, B0); PG8_MMA(0, 1, At, B1); PG8_BAR; PG8_SCHED;
;             PG8_LDA(At, 0, 1); PG8_STAGE(PG8_SB(0, 0), b2, voffB); PG8_STAGE(PG8_SB(0, 1), b2 + hstep, voffB); PG8_STAGE(PG8_SA(0, 0), a2, voffA);
;             PG8_WAIT_V(8); PG8_WAIT_L(0); PG8_BAR; PG8_MMA(1, 0, At, B0); PG8_MMA(1, 1, At, B1); PG8_BAR; PG8_SCHED;
.Lvmw_181_0:
	s_waitcnt lgkmcnt(0)
	s_barrier
	s_waitcnt lgkmcnt(0)
	v_mfma_f32_16x16x32_f16 v[124:127], v[172:175], v[204:207], 0
	v_mfma_f32_16x16x32_f16 v[116:119], v[180:183], v[204:207], 0
	v_mfma_f32_16x16x32_f16 v[108:111], v[172:175], v[212:215], 0
	v_mfma_f32_16x16x32_f16 v[104:107], v[180:183], v[212:215], 0
	v_mfma_f32_16x16x32_f16 v[92:95], v[172:175], v[220:223], 0
	v_mfma_f32_16x16x32_f16 v[88:91], v[180:183], v[220:223], 0
	v_mfma_f32_16x16x32_f16 v[76:79], v[172:175], v[232:235], 0
	v_mfma_f32_16x16x32_f16 v[72:75], v[180:183], v[232:235], 0
	v_mfma_f32_16x16x32_f16 v[124:127], v[176:179], v[208:211], v[124:127]
	v_mfma_f32_16x16x32_f16 v[116:119], v[184:187], v[208:211], v[116:119]
	v_mfma_f32_16x16x32_f16 v[108:111], v[176:179], v[216:219], v[108:111]
	v_mfma_f32_16x16x32_f16 v[104:107], v[184:187], v[216:219], v[104:107]
	v_mfma_f32_16x16x32_f16 v[92:95], v[176:179], v[228:231], v[92:95]
	v_mfma_f32_16x16x32_f16 v[88:91], v[184:187], v[228:231], v[88:91]
	v_mfma_f32_16x16x32_f16 v[76:79], v[176:179], v[236:239], v[76:79]
	v_mfma_f32_16x16x32_f16 v[72:75], v[184:187], v[236:239], v[72:75]
	v_mfma_f32_16x16x32_f16 v[120:123], v[188:191], v[204:207], 0
	v_mfma_f32_16x16x32_f16 v[112:115], v[196:199], v[204:207], 0
	v_mfma_f32_16x16x32_f16 v[100:103], v[188:191], v[212:215], 0
	v_mfma_f32_16x16x32_f16 v[96:99], v[196:199], v[212:215], 0
	v_mfma_f32_16x16x32_f16 v[84:87], v[188:191], v[220:223], 0
	v_mfma_f32_16x16x32_f16 v[80:83], v[196:199], v[220:223], 0
	v_mfma_f32_16x16x32_f16 v[68:71], v[188:191], v[232:235], 0
	v_mfma_f32_16x16x32_f16 v[64:67], v[196:199], v[232:235], 0
	v_mfma_f32_16x16x32_f16 v[120:123], v[192:195], v[208:211], v[120:123]
	v_mfma_f32_16x16x32_f16 v[112:115], v[200:203], v[208:211], v[112:115]
	v_mfma_f32_16x16x32_f16 v[100:103], v[192:195], v[216:219], v[100:103]
	v_mfma_f32_16x16x32_f16 v[96:99], v[200:203], v[216:219], v[96:99]
	v_mfma_f32_16x16x32_f16 v[84:87], v[192:195], v[228:231], v[84:87]
	v_mfma_f32_16x16x32_f16 v[80:83], v[200:203], v[228:231], v[80:83]
	v_mfma_f32_16x16x32_f16 v[68:71], v[192:195], v[236:239], v[68:71]
	v_mfma_f32_16x16x32_f16 v[64:67], v[200:203], v[236:239], v[64:67]
	s_barrier
	s_mov_b32 m0, s37
	v_lshl_add_u64 v[148:149], s[8:9], 0, v[132:133]
	s_add_u32 s82, s8, 0x40000
	ds_read_b128 v[204:207], v153 offset:16384
	ds_read_b128 v[208:211], v153 offset:17408
	ds_read_b128 v[212:215], v153 offset:18432
	ds_read_b128 v[216:219], v153 offset:19456
	ds_read_b128 v[220:223], v153 offset:20480
	ds_read_b128 v[228:231], v153 offset:21504
	ds_read_b128 v[232:235], v153 offset:22528
	ds_read_b128 v[236:239], v153 offset:23552
	global_load_lds_dwordx4 v[148:149], off
	v_lshl_add_u64 v[224:225], s[8:9], 0, v[128:129]
	s_mov_b32 m0, s45
	s_addc_u32 s83, s9, 0
	global_load_lds_dwordx4 v[224:225], off
	v_lshl_add_u64 v[240:241], s[82:83], 0, v[132:133]
	s_mov_b32 m0, s58
	v_lshl_add_u64 v[242:243], s[56:57], 0, v[130:131]
	global_load_lds_dwordx4 v[240:241], off
	v_lshl_add_u64 v[240:241], s[82:83], 0, v[128:129]
	s_mov_b32 m0, s59
	s_nop 0
	global_load_lds_dwordx4 v[240:241], off
	v_lshl_add_u64 v[240:241], s[56:57], 0, v[134:135]
	s_mov_b32 m0, s20
	s_nop 0
	global_load_lds_dwordx4 v[240:241], off
	s_mov_b32 m0, s60
	s_nop 0
	global_load_lds_dwordx4 v[242:243], off
	s_waitcnt vmcnt(16)
	s_cmp_lg_u32 s99, -1
	s_cbranch_scc1 .Lvmw_181_1
	s_waitcnt vmcnt(8)
.Lvmw_181_1:
	s_waitcnt lgkmcnt(0)
	s_barrier
	s_waitcnt lgkmcnt(0)
	v_mfma_f32_16x16x32_f16 v[60:63], v[172:175], v[204:207], 0
	v_mfma_f32_16x16x32_f16 v[56:59], v[180:183], v[204:207], 0
	v_mfma_f32_16x16x32_f16 v[44:47], v[172:175], v[212:215], 0
	v_mfma_f32_16x16x32_f16 v[40:43], v[180:183], v[212:215], 0
	v_mfma_f32_16x16x32_f16 v[28:31], v[172:175], v[220:223], 0
	v_mfma_f32_16x16x32_f16 v[24:27], v[180:183], v[220:223], 0
	v_mfma_f32_16x16x32_f16 v[12:15], v[172:175], v[232:235], 0
	v_mfma_f32_16x16x32_f16 v[8:11], v[180:183], v[232:235], 0
	v_mfma_f32_16x16x32_f16 v[60:63], v[176:179], v[208:211], v[60:63]
	v_mfma_f32_16x16x32_f16 v[56:59], v[184:187], v[208:211], v[56:59]
	v_mfma_f32_16x16x32_f16 v[44:47], v[176:179], v[216:219], v[44:47]
	v_mfma_f32_16x16x32_f16 v[40:43], v[184:187], v[216:219], v[40:43]
	v_mfma_f32_16x16x32_f16 v[28:31], v[176:179], v[228:231], v[28:31]
	v_mfma_f32_16x16x32_f16 v[24:27], v[184:187], v[228:231], v[24:27]
	v_mfma_f32_16x16x32_f16 v[12:15], v[176:179], v[236:239], v[12:15]
	v_mfma_f32_16x16x32_f16 v[8:11], v[184:187], v[236:239], v[8:11]
	v_mfma_f32_16x16x32_f16 v[52:55], v[188:191], v[204:207], 0
	v_mfma_f32_16x16x32_f16 v[48:51], v[196:199], v[204:207], 0
	v_mfma_f32_16x16x32_f16 v[36:39], v[188:191], v[212:215], 0
	v_mfma_f32_16x16x32_f16 v[32:35], v[196:199], v[212:215], 0
	v_mfma_f32_16x16x32_f16 v[20:23], v[188:191], v[220:223], 0
	v_mfma_f32_16x16x32_f16 v[16:19], v[196:199], v[220:223], 0
	v_mfma_f32_16x16x32_f16 v[4:7], v[188:191], v[232:235], 0
	v_mfma_f32_16x16x32_f16 v[0:3], v[196:199], v[232:235], 0
	v_mfma_f32_16x16x32_f16 v[52:55], v[192:195], v[208:211], v[52:55]
	v_mfma_f32_16x16x32_f16 v[48:51], v[200:203], v[208:211], v[48:51]
	v_mfma_f32_16x16x32_f16 v[36:39], v[192:195], v[216:219], v[36:39]
	v_mfma_f32_16x16x32_f16 v[32:35], v[200:203], v[216:219], v[32:35]
	v_mfma_f32_16x16x32_f16 v[20:23], v[192:195], v[228:231], v[20:23]
	v_mfma_f32_16x16x32_f16 v[16:19], v[200:203], v[228:231], v[16:19]
	v_mfma_f32_16x16x32_f16 v[4:7], v[192:195], v[236:239], v[4:7]
	v_mfma_f32_16x16x32_f16 v[0:3], v[200:203], v[236:239], v[0:3]
	s_barrier
; #define PG8_STAGE(bufoff, gbase, voff) do { _Pragma("unroll") for (int _i = 0; _i < 2; ++_i) \
;         __builtin_amdgcn_global_load_lds((const unsigned*)((const char*)(gbase) + (voff)[_i]), (PG8_LAS unsigned*)(lds + (bufoff) + ldsw + _i * 8192), 16, 0, 0); } while (0)
; #define PG8_LDA(dst, b, h) do { _Pragma("unroll") for (int m = 0; m < 4; ++m) _Pragma("unroll") for (int k = 0; k < 2; ++k) dst[m][k] = *(const PG8_LAS bf16x8*)(lds + PG8_SA(b, h) + aoff + m * 2048 + k * 1024); } while (0)
; #define PG8_LDB(dst, b, h) do { _Pragma("unroll") for (int n = 0; n < 2; ++n) _Pragma("unroll") for (int k = 0; k < 2; ++k) dst[n][k] = *(const PG8_LAS bf16x8*)(lds + PG8_SB(b, h) + boff + n * 2048 + k * 1024); } while (0)
; #define PG8_MMA(ai, bj, At, Bt) do { __builtin_amdgcn_s_setprio(1); _Pragma("unroll") for (int m = 0; m < 4; ++m) _Pragma("unroll") for (int n = 0; n < 2; ++n) _Pragma("unroll") for (int k = 0; k < 2; ++k) \
;         acc[ai][bj][m][n] = mma16<F16>(Bt[n][k], At[m][k], acc[ai][bj][m][n]); __builtin_amdgcn_s_setprio(0); } while (0)
; #define PG8_WAIT_V(n) asm volatile("s_waitcnt vmcnt(" #n ")" ::: "memory")
; #define PG8_WAIT_L(n) asm volatile("s_waitcnt lgkmcnt(" #n ")" ::: "memory")
; #define PG8_BAR __builtin_amdgcn_s_barrier()
; #define PG8_SCHED __builtin_amdgcn_sched_barrier(0)
; template <class Epi, class Sched, bool ALIGN_EPI = false, bool SP2 = false, bool F16 = false, bool TOKPERM = false>
; __device__ __forceinline__ void gemm_phase(PG8_LAS unsigned char* lds, const Gemm g, const Sched& S, const Epi& E, int wv) {
;     ...
;         for (int t = 0; t < nt; t += 2) {
;     ...
;             PG8_LDB(B0, 1, 0); PG8_LDB(B1, 1, 1); PG8_SCHED; PG8_LDA(At, 1, 0); PG8_STAGE(PG8_SA(0, 1), a2 + hstep, voffA);
;             PG8_WAIT_V(8); PG8_WAIT_L(0); PG8_BAR; PG8_MMA(0, 0, At, B0); PG8_MMA(0, 1, At, B1); PG8_BAR; PG8_SCHED;
;             PG8_LDA(At, 1, 1); PG8_STAGE(PG8_SB(1, 0), b3, voffB); PG8_STAGE(PG8_SB(1, 1), b3 + hstep, voffB); PG8_STAGE(PG8_SA(1, 0), a3, voffA);
;             PG8_WAIT_V(8); PG8_WAIT_L(0); PG8_BAR; PG8_MMA(1, 0, At, B0); PG8_MMA(1, 1, At, B1); PG8_BAR; PG8_SCHED;
	ds_read_b128 v[172:175], v163
	ds_read_b128 v[176:179], v164
	ds_read_b128 v[180:183], v165
	ds_read_b128 v[184:187], v166
	ds_read_b128 v[188:191], v167
	ds_read_b128 v[192:195], v168
	ds_read_b128 v[196:199], v169
	ds_read_b128 v[200:203], v170
	s_add_u32 s56, s56, 0x40000
	s_addc_u32 s57, s57, 0
	s_mov_b32 m0, s61
	v_lshl_add_u64 v[244:245], s[56:57], 0, v[134:135]
	ds_read_b128 v[204:207], v153 offset:32768
	ds_read_b128 v[208:211], v153 offset:33792
	ds_read_b128 v[212:215], v153 offset:34816
	ds_read_b128 v[216:219], v153 offset:35840
	ds_read_b128 v[220:223], v153 offset:36864
	ds_read_b128 v[228:231], v153 offset:37888
	ds_read_b128 v[232:235], v153 offset:38912
	ds_read_b128 v[236:239], v153 offset:39936
	global_load_lds_dwordx4 v[244:245], off
	v_lshl_add_u64 v[244:245], s[56:57], 0, v[130:131]
	s_mov_b32 m0, s62
	s_nop 0
	global_load_lds_dwordx4 v[244:245], off
	s_waitcnt vmcnt(8)
	s_waitcnt lgkmcnt(0)
	s_barrier
	s_waitcnt lgkmcnt(0)
	v_mfma_f32_16x16x32_f16 v[124:127], v[172:175], v[204:207], v[124:127]
	v_mfma_f32_16x16x32_f16 v[116:119], v[180:183], v[204:207], v[116:119]
	v_mfma_f32_16x16x32_f16 v[108:111], v[172:175], v[212:215], v[108:111]
	v_mfma_f32_16x16x32_f16 v[104:107], v[180:183], v[212:215], v[104:107]
	v_mfma_f32_16x16x32_f16 v[92:95], v[172:175], v[220:223], v[92:95]
	v_mfma_f32_16x16x32_f16 v[88:91], v[180:183], v[220:223], v[88:91]
	v_mfma_f32_16x16x32_f16 v[76:79], v[172:175], v[232:235], v[76:79]
	v_mfma_f32_16x16x32_f16 v[72:75], v[180:183], v[232:235], v[72:75]
	v_mfma_f32_16x16x32_f16 v[124:127], v[176:179], v[208:211], v[124:127]
	v_mfma_f32_16x16x32_f16 v[116:119], v[184:187], v[208:211], v[116:119]
	v_mfma_f32_16x16x32_f16 v[108:111], v[176:179], v[216:219], v[108:111]
	v_mfma_f32_16x16x32_f16 v[104:107], v[184:187], v[216:219], v[104:107]
	v_mfma_f32_16x16x32_f16 v[92:95], v[176:179], v[228:231], v[92:95]
	v_mfma_f32_16x16x32_f16 v[88:91], v[184:187], v[228:231], v[88:91]
	v_mfma_f32_16x16x32_f16 v[76:79], v[176:179], v[236:239], v[76:79]
	v_mfma_f32_16x16x32_f16 v[72:75], v[184:187], v[236:239], v[72:75]
	v_mfma_f32_16x16x32_f16 v[120:123], v[188:191], v[204:207], v[120:123]
	v_mfma_f32_16x16x32_f16 v[112:115], v[196:199], v[204:207], v[112:115]
	v_mfma_f32_16x16x32_f16 v[100:103], v[188:191], v[212:215], v[100:103]
	v_mfma_f32_16x16x32_f16 v[96:99], v[196:199], v[212:215], v[96:99]
	v_mfma_f32_16x16x32_f16 v[84:87], v[188:191], v[220:223], v[84:87]
	v_mfma_f32_16x16x32_f16 v[80:83], v[196:199], v[220:223], v[80:83]
	v_mfma_f32_16x16x32_f16 v[68:71], v[188:191], v[232:235], v[68:71]
	v_mfma_f32_16x16x32_f16 v[64:67], v[196:199], v[232:235], v[64:67]
	v_mfma_f32_16x16x32_f16 v[120:123], v[192:195], v[208:211], v[120:123]
	v_mfma_f32_16x16x32_f16 v[112:115], v[200:203], v[208:211], v[112:115]
	v_mfma_f32_16x16x32_f16 v[100:103], v[192:195], v[216:219], v[100:103]
	v_mfma_f32_16x16x32_f16 v[96:99], v[200:203], v[216:219], v[96:99]
	v_mfma_f32_16x16x32_f16 v[84:87], v[192:195], v[228:231], v[84:87]
	v_mfma_f32_16x16x32_f16 v[80:83], v[200:203], v[228:231], v[80:83]
	v_mfma_f32_16x16x32_f16 v[68:71], v[192:195], v[236:239], v[68:71]
	v_mfma_f32_16x16x32_f16 v[64:67], v[200:203], v[236:239], v[64:67]
	s_barrier
	s_mov_b32 m0, s64
	v_lshl_add_u64 v[148:149], v[148:149], 0, s[16:17]
	s_add_u32 s8, s8, 0x40080
	ds_read_b128 v[204:207], v153 offset:49152
	ds_read_b128 v[208:211], v153 offset:50176
	ds_read_b128 v[212:215], v153 offset:51200
	ds_read_b128 v[216:219], v153 offset:52224
	ds_read_b128 v[220:223], v153 offset:53248
	ds_read_b128 v[228:231], v153 offset:54272
	ds_read_b128 v[232:235], v153 offset:55296
	ds_read_b128 v[236:239], v153 offset:56320
	global_load_lds_dwordx4 v[148:149], off
	v_lshl_add_u64 v[148:149], v[224:225], 0, s[16:17]
	s_mov_b32 m0, s65
	s_addc_u32 s9, s9, 0
	global_load_lds_dwordx4 v[148:149], off
	v_lshl_add_u64 v[148:149], s[8:9], 0, v[132:133]
	s_mov_b32 m0, s69
	s_nop 0
	global_load_lds_dwordx4 v[148:149], off
	v_lshl_add_u64 v[148:149], s[8:9], 0, v[128:129]
	s_mov_b32 m0, s70
	s_nop 0
	global_load_lds_dwordx4 v[148:149], off
	v_lshl_add_u64 v[148:149], v[240:241], 0, s[16:17]
	s_mov_b32 m0, s66
	s_nop 0
	global_load_lds_dwordx4 v[148:149], off
	v_lshl_add_u64 v[148:149], v[242:243], 0, s[16:17]
	s_mov_b32 m0, s68
	s_nop 0
	global_load_lds_dwordx4 v[148:149], off
	s_waitcnt vmcnt(8)
	s_waitcnt lgkmcnt(0)
	s_barrier
	s_waitcnt lgkmcnt(0)
	v_mfma_f32_16x16x32_f16 v[60:63], v[172:175], v[204:207], v[60:63]
	v_mfma_f32_16x16x32_f16 v[56:59], v[180:183], v[204:207], v[56:59]
	v_mfma_f32_16x16x32_f16 v[44:47], v[172:175], v[212:215], v[44:47]
	v_mfma_f32_16x16x32_f16 v[40:43], v[180:183], v[212:215], v[40:43]
	v_mfma_f32_16x16x32_f16 v[28:31], v[172:175], v[220:223], v[28:31]
	v_mfma_f32_16x16x32_f16 v[24:27], v[180:183], v[220:223], v[24:27]
	v_mfma_f32_16x16x32_f16 v[12:15], v[172:175], v[232:235], v[12:15]
	v_mfma_f32_16x16x32_f16 v[8:11], v[180:183], v[232:235], v[8:11]
	v_mfma_f32_16x16x32_f16 v[60:63], v[176:179], v[208:211], v[60:63]
	v_mfma_f32_16x16x32_f16 v[56:59], v[184:187], v[208:211], v[56:59]
	v_mfma_f32_16x16x32_f16 v[44:47], v[176:179], v[216:219], v[44:47]
	v_mfma_f32_16x16x32_f16 v[40:43], v[184:187], v[216:219], v[40:43]
	v_mfma_f32_16x16x32_f16 v[28:31], v[176:179], v[228:231], v[28:31]
	v_mfma_f32_16x16x32_f16 v[24:27], v[184:187], v[228:231], v[24:27]
	v_mfma_f32_16x16x32_f16 v[12:15], v[176:179], v[236:239], v[12:15]
	v_mfma_f32_16x16x32_f16 v[8:11], v[184:187], v[236:239], v[8:11]
	v_mfma_f32_16x16x32_f16 v[52:55], v[188:191], v[204:207], v[52:55]
	v_mfma_f32_16x16x32_f16 v[48:51], v[196:199], v[204:207], v[48:51]
	v_mfma_f32_16x16x32_f16 v[36:39], v[188:191], v[212:215], v[36:39]
	v_mfma_f32_16x16x32_f16 v[32:35], v[196:199], v[212:215], v[32:35]
	v_mfma_f32_16x16x32_f16 v[20:23], v[188:191], v[220:223], v[20:23]
	v_mfma_f32_16x16x32_f16 v[16:19], v[196:199], v[220:223], v[16:19]
	v_mfma_f32_16x16x32_f16 v[4:7], v[188:191], v[232:235], v[4:7]
	v_mfma_f32_16x16x32_f16 v[0:3], v[196:199], v[232:235], v[0:3]
	v_mfma_f32_16x16x32_f16 v[52:55], v[192:195], v[208:211], v[52:55]
	v_mfma_f32_16x16x32_f16 v[48:51], v[200:203], v[208:211], v[48:51]
	v_mfma_f32_16x16x32_f16 v[36:39], v[192:195], v[216:219], v[36:39]
	v_mfma_f32_16x16x32_f16 v[32:35], v[200:203], v[216:219], v[32:35]
	v_mfma_f32_16x16x32_f16 v[20:23], v[192:195], v[228:231], v[20:23]
	v_mfma_f32_16x16x32_f16 v[16:19], v[200:203], v[228:231], v[16:19]
	v_mfma_f32_16x16x32_f16 v[4:7], v[192:195], v[236:239], v[4:7]
	v_mfma_f32_16x16x32_f16 v[0:3], v[200:203], v[236:239], v[0:3]
	s_barrier
	s_add_i32 s81, s81, 2
	s_add_u32 s6, s6, 0x100
	s_addc_u32 s7, s7, 0
	s_add_u32 s79, s79, 0x100
	s_addc_u32 s80, s80, 0
	s_cmp_gt_u32 s81, 13

; #define PG8_STAGE(bufoff, gbase, voff) do { _Pragma("unroll") for (int _i = 0; _i < 2; ++_i) \
;         __builtin_amdgcn_global_load_lds((const unsigned*)((const char*)(gbase) + (voff)[_i]), (PG8_LAS unsigned*)(lds + (bufoff) + ldsw + _i * 8192), 16, 0, 0); } while (0)
; #define PG8_LDA(dst, b, h) do { _Pragma("unroll") for (int m = 0; m < 4; ++m) _Pragma("unroll") for (int k = 0; k < 2; ++k) dst[m][k] = *(const PG8_LAS bf16x8*)(lds + PG8_SA(b, h) + aoff + m * 2048 + k * 1024); } while (0)
; #define PG8_MMA(ai, bj, At, Bt) do { __builtin_amdgcn_s_setprio(1); _Pragma("unroll") for (int m = 0; m < 4; ++m) _Pragma("unroll") for (int n = 0; n < 2; ++n) _Pragma("unroll") for (int k = 0; k < 2; ++k) \
;         acc[ai][bj][m][n] = mma16<F16>(Bt[n][k], At[m][k], acc[ai][bj][m][n]); __builtin_amdgcn_s_setprio(0); } while (0)
; #define PG8_WAIT_V(n) asm volatile("s_waitcnt vmcnt(" #n ")" ::: "memory")
; #define PG8_WAIT_L(n) asm volatile("s_waitcnt lgkmcnt(" #n ")" ::: "memory")
; #define PG8_BAR __builtin_amdgcn_s_barrier()
; #define PG8_SCHED __builtin_amdgcn_sched_barrier(0)
; template <class Epi, class Sched, bool ALIGN_EPI = false, bool SP2 = false, bool F16 = false, bool TOKPERM = false>
; __device__ __forceinline__ void gemm_phase(PG8_LAS unsigned char* lds, const Gemm g, const Sched& S, const Epi& E, int wv) {
;     ...
;             PG8_WAIT_V(8); PG8_WAIT_L(0); PG8_BAR; PG8_MMA(0, 0, At, B0); PG8_MMA(0, 1, At, B1); PG8_BAR; PG8_SCHED;
;             PG8_LDA(At, 0, 1); PG8_STAGE(PG8_SB(0, 0), b2, voffB); PG8_STAGE(PG8_SB(0, 1), b2 + hstep, voffB); PG8_STAGE(PG8_SA(0, 0), a2, voffA);
;             PG8_WAIT_V(8); PG8_WAIT_L(0); PG8_BAR; PG8_MMA(1, 0, At, B0); PG8_MMA(1, 1, At, B1); PG8_BAR; PG8_SCHED;
.Lvmw_768_0:
	s_waitcnt lgkmcnt(0)
	s_barrier
	s_waitcnt lgkmcnt(0)
	v_mfma_f32_16x16x32_f16 v[124:127], v[172:175], v[204:207], 0
	v_mfma_f32_16x16x32_f16 v[116:119], v[180:183], v[204:207], 0
	v_mfma_f32_16x16x32_f16 v[108:111], v[172:175], v[212:215], 0
	v_mfma_f32_16x16x32_f16 v[104:107], v[180:183], v[212:215], 0
	v_mfma_f32_16x16x32_f16 v[92:95], v[172:175], v[220:223], 0
	v_mfma_f32_16x16x32_f16 v[88:91], v[180:183], v[220:223], 0
	v_mfma_f32_16x16x32_f16 v[76:79], v[172:175], v[232:235], 0
	v_mfma_f32_16x16x32_f16 v[72:75], v[180:183], v[232:235], 0
	v_mfma_f32_16x16x32_f16 v[124:127], v[176:179], v[208:211], v[124:127]
	v_mfma_f32_16x16x32_f16 v[116:119], v[184:187], v[208:211], v[116:119]
	v_mfma_f32_16x16x32_f16 v[108:111], v[176:179], v[216:219], v[108:111]
	v_mfma_f32_16x16x32_f16 v[104:107], v[184:187], v[216:219], v[104:107]
	v_mfma_f32_16x16x32_f16 v[92:95], v[176:179], v[228:231], v[92:95]
	v_mfma_f32_16x16x32_f16 v[88:91], v[184:187], v[228:231], v[88:91]
	v_mfma_f32_16x16x32_f16 v[76:79], v[176:179], v[236:239], v[76:79]
	v_mfma_f32_16x16x32_f16 v[72:75], v[184:187], v[236:239], v[72:75]
	v_mfma_f32_16x16x32_f16 v[120:123], v[188:191], v[204:207], 0
	v_mfma_f32_16x16x32_f16 v[112:115], v[196:199], v[204:207], 0
	v_mfma_f32_16x16x32_f16 v[100:103], v[188:191], v[212:215], 0
	v_mfma_f32_16x16x32_f16 v[96:99], v[196:199], v[212:215], 0
	v_mfma_f32_16x16x32_f16 v[84:87], v[188:191], v[220:223], 0
	v_mfma_f32_16x16x32_f16 v[80:83], v[196:199], v[220:223], 0
	v_mfma_f32_16x16x32_f16 v[68:71], v[188:191], v[232:235], 0
	v_mfma_f32_16x16x32_f16 v[64:67], v[196:199], v[232:235], 0
	v_mfma_f32_16x16x32_f16 v[120:123], v[192:195], v[208:211], v[120:123]
	v_mfma_f32_16x16x32_f16 v[112:115], v[200:203], v[208:211], v[112:115]
	v_mfma_f32_16x16x32_f16 v[100:103], v[192:195], v[216:219], v[100:103]
	v_mfma_f32_16x16x32_f16 v[96:99], v[200:203], v[216:219], v[96:99]
	v_mfma_f32_16x16x32_f16 v[84:87], v[192:195], v[228:231], v[84:87]
	v_mfma_f32_16x16x32_f16 v[80:83], v[200:203], v[228:231], v[80:83]
	v_mfma_f32_16x16x32_f16 v[68:71], v[192:195], v[236:239], v[68:71]
	v_mfma_f32_16x16x32_f16 v[64:67], v[200:203], v[236:239], v[64:67]
	s_barrier
	s_mov_b32 m0, s5
	v_lshl_add_u64 v[148:149], s[12:13], 0, v[132:133]
	s_add_u32 s76, s12, 0x40000
	ds_read_b128 v[204:207], v153 offset:16384
	ds_read_b128 v[208:211], v153 offset:17408
	ds_read_b128 v[212:215], v153 offset:18432
	ds_read_b128 v[216:219], v153 offset:19456
	ds_read_b128 v[220:223], v153 offset:20480
	ds_read_b128 v[228:231], v153 offset:21504
	ds_read_b128 v[232:235], v153 offset:22528
	ds_read_b128 v[236:239], v153 offset:23552
	global_load_lds_dwordx4 v[148:149], off
	v_lshl_add_u64 v[224:225], s[12:13], 0, v[128:129]
	s_mov_b32 m0, s21
	s_addc_u32 s77, s13, 0
	global_load_lds_dwordx4 v[224:225], off
	v_lshl_add_u64 v[240:241], s[76:77], 0, v[132:133]
	s_mov_b32 m0, s22
	v_lshl_add_u64 v[242:243], s[58:59], 0, v[130:131]
	global_load_lds_dwordx4 v[240:241], off
	v_lshl_add_u64 v[240:241], s[76:77], 0, v[128:129]
	s_mov_b32 m0, s23
	s_nop 0
	global_load_lds_dwordx4 v[240:241], off
	v_lshl_add_u64 v[240:241], s[58:59], 0, v[134:135]
	s_mov_b32 m0, s2
	s_nop 0
	global_load_lds_dwordx4 v[240:241], off
	s_mov_b32 m0, s33
	s_nop 0
	global_load_lds_dwordx4 v[242:243], off
	s_waitcnt vmcnt(16)
	s_cmp_lg_u32 s99, -1
	s_cbranch_scc1 .Lvmw_768_1
	s_waitcnt vmcnt(8)
.Lvmw_768_1:
	s_waitcnt lgkmcnt(0)
	s_barrier
	s_waitcnt lgkmcnt(0)
	v_mfma_f32_16x16x32_f16 v[60:63], v[172:175], v[204:207], 0
	v_mfma_f32_16x16x32_f16 v[56:59], v[180:183], v[204:207], 0
	v_mfma_f32_16x16x32_f16 v[44:47], v[172:175], v[212:215], 0
	v_mfma_f32_16x16x32_f16 v[40:43], v[180:183], v[212:215], 0
	v_mfma_f32_16x16x32_f16 v[28:31], v[172:175], v[220:223], 0
	v_mfma_f32_16x16x32_f16 v[24:27], v[180:183], v[220:223], 0
	v_mfma_f32_16x16x32_f16 v[12:15], v[172:175], v[232:235], 0
	v_mfma_f32_16x16x32_f16 v[8:11], v[180:183], v[232:235], 0
	v_mfma_f32_16x16x32_f16 v[60:63], v[176:179], v[208:211], v[60:63]
	v_mfma_f32_16x16x32_f16 v[56:59], v[184:187], v[208:211], v[56:59]
	v_mfma_f32_16x16x32_f16 v[44:47], v[176:179], v[216:219], v[44:47]
	v_mfma_f32_16x16x32_f16 v[40:43], v[184:187], v[216:219], v[40:43]
	v_mfma_f32_16x16x32_f16 v[28:31], v[176:179], v[228:231], v[28:31]
	v_mfma_f32_16x16x32_f16 v[24:27], v[184:187], v[228:231], v[24:27]
	v_mfma_f32_16x16x32_f16 v[12:15], v[176:179], v[236:239], v[12:15]
	v_mfma_f32_16x16x32_f16 v[8:11], v[184:187], v[236:239], v[8:11]
	v_mfma_f32_16x16x32_f16 v[52:55], v[188:191], v[204:207], 0
	v_mfma_f32_16x16x32_f16 v[48:51], v[196:199], v[204:207], 0
	v_mfma_f32_16x16x32_f16 v[36:39], v[188:191], v[212:215], 0
	v_mfma_f32_16x16x32_f16 v[32:35], v[196:199], v[212:215], 0
	v_mfma_f32_16x16x32_f16 v[20:23], v[188:191], v[220:223], 0
	v_mfma_f32_16x16x32_f16 v[16:19], v[196:199], v[220:223], 0
	v_mfma_f32_16x16x32_f16 v[4:7], v[188:191], v[232:235], 0
	v_mfma_f32_16x16x32_f16 v[0:3], v[196:199], v[232:235], 0
	v_mfma_f32_16x16x32_f16 v[52:55], v[192:195], v[208:211], v[52:55]
	v_mfma_f32_16x16x32_f16 v[48:51], v[200:203], v[208:211], v[48:51]
	v_mfma_f32_16x16x32_f16 v[36:39], v[192:195], v[216:219], v[36:39]
	v_mfma_f32_16x16x32_f16 v[32:35], v[200:203], v[216:219], v[32:35]
	v_mfma_f32_16x16x32_f16 v[20:23], v[192:195], v[228:231], v[20:23]
	v_mfma_f32_16x16x32_f16 v[16:19], v[200:203], v[228:231], v[16:19]
	v_mfma_f32_16x16x32_f16 v[4:7], v[192:195], v[236:239], v[4:7]
	v_mfma_f32_16x16x32_f16 v[0:3], v[200:203], v[236:239], v[0:3]
	s_barrier
; #define PG8_STAGE(bufoff, gbase, voff) do { _Pragma("unroll") for (int _i = 0; _i < 2; ++_i) \
;         __builtin_amdgcn_global_load_lds((const unsigned*)((const char*)(gbase) + (voff)[_i]), (PG8_LAS unsigned*)(lds + (bufoff) + ldsw + _i * 8192), 16, 0, 0); } while (0)
; #define PG8_LDA(dst, b, h) do { _Pragma("unroll") for (int m = 0; m < 4; ++m) _Pragma("unroll") for (int k = 0; k < 2; ++k) dst[m][k] = *(const PG8_LAS bf16x8*)(lds + PG8_SA(b, h) + aoff + m * 2048 + k * 1024); } while (0)
; #define PG8_LDB(dst, b, h) do { _Pragma("unroll") for (int n = 0; n < 2; ++n) _Pragma("unroll") for (int k = 0; k < 2; ++k) dst[n][k] = *(const PG8_LAS bf16x8*)(lds + PG8_SB(b, h) + boff + n * 2048 + k * 1024); } while (0)
; #define PG8_MMA(ai, bj, At, Bt) do { __builtin_amdgcn_s_setprio(1); _Pragma("unroll") for (int m = 0; m < 4; ++m) _Pragma("unroll") for (int n = 0; n < 2; ++n) _Pragma("unroll") for (int k = 0; k < 2; ++k) \
;         acc[ai][bj][m][n] = mma16<F16>(Bt[n][k], At[m][k], acc[ai][bj][m][n]); __builtin_amdgcn_s_setprio(0); } while (0)
; #define PG8_WAIT_V(n) asm volatile("s_waitcnt vmcnt(" #n ")" ::: "memory")
; #define PG8_WAIT_L(n) asm volatile("s_waitcnt lgkmcnt(" #n ")" ::: "memory")
; #define PG8_BAR __builtin_amdgcn_s_barrier()
; #define PG8_SCHED __builtin_amdgcn_sched_barrier(0)
; template <class Epi, class Sched, bool ALIGN_EPI = false, bool SP2 = false, bool F16 = false, bool TOKPERM = false>
; __device__ __forceinline__ void gemm_phase(PG8_LAS unsigned char* lds, const Gemm g, const Sched& S, const Epi& E, int wv) {
;     ...
;         for (int t = 0; t < nt; t += 2) {
;     ...
;             PG8_LDB(B0, 1, 0); PG8_LDB(B1, 1, 1); PG8_SCHED; PG8_LDA(At, 1, 0); PG8_STAGE(PG8_SA(0, 1), a2 + hstep, voffA);
;             PG8_WAIT_V(8); PG8_WAIT_L(0); PG8_BAR; PG8_MMA(0, 0, At, B0); PG8_MMA(0, 1, At, B1); PG8_BAR; PG8_SCHED;
;             PG8_LDA(At, 1, 1); PG8_STAGE(PG8_SB(1, 0), b3, voffB); PG8_STAGE(PG8_SB(1, 1), b3 + hstep, voffB); PG8_STAGE(PG8_SA(1, 0), a3, voffA);
;             PG8_WAIT_V(8); PG8_WAIT_L(0); PG8_BAR; PG8_MMA(1, 0, At, B0); PG8_MMA(1, 1, At, B1); PG8_BAR; PG8_SCHED;
	ds_read_b128 v[172:175], v163
	ds_read_b128 v[176:179], v164
	ds_read_b128 v[180:183], v165
	ds_read_b128 v[184:187], v166
	ds_read_b128 v[188:191], v167
	ds_read_b128 v[192:195], v168
	ds_read_b128 v[196:199], v169
	ds_read_b128 v[200:203], v170
	s_add_u32 s58, s58, 0x40000
	s_addc_u32 s59, s59, 0
	s_mov_b32 m0, s36
	v_lshl_add_u64 v[244:245], s[58:59], 0, v[134:135]
	ds_read_b128 v[204:207], v153 offset:32768
	ds_read_b128 v[208:211], v153 offset:33792
	ds_read_b128 v[212:215], v153 offset:34816
	ds_read_b128 v[216:219], v153 offset:35840
	ds_read_b128 v[220:223], v153 offset:36864
	ds_read_b128 v[228:231], v153 offset:37888
	ds_read_b128 v[232:235], v153 offset:38912
	ds_read_b128 v[236:239], v153 offset:39936
	global_load_lds_dwordx4 v[244:245], off
	v_lshl_add_u64 v[244:245], s[58:59], 0, v[130:131]
	s_mov_b32 m0, s37
	s_nop 0
	global_load_lds_dwordx4 v[244:245], off
	s_waitcnt vmcnt(8)
	s_waitcnt lgkmcnt(0)
	s_barrier
	s_waitcnt lgkmcnt(0)
	v_mfma_f32_16x16x32_f16 v[124:127], v[172:175], v[204:207], v[124:127]
	v_mfma_f32_16x16x32_f16 v[116:119], v[180:183], v[204:207], v[116:119]
	v_mfma_f32_16x16x32_f16 v[108:111], v[172:175], v[212:215], v[108:111]
	v_mfma_f32_16x16x32_f16 v[104:107], v[180:183], v[212:215], v[104:107]
	v_mfma_f32_16x16x32_f16 v[92:95], v[172:175], v[220:223], v[92:95]
	v_mfma_f32_16x16x32_f16 v[88:91], v[180:183], v[220:223], v[88:91]
	v_mfma_f32_16x16x32_f16 v[76:79], v[172:175], v[232:235], v[76:79]
	v_mfma_f32_16x16x32_f16 v[72:75], v[180:183], v[232:235], v[72:75]
	v_mfma_f32_16x16x32_f16 v[124:127], v[176:179], v[208:211], v[124:127]
	v_mfma_f32_16x16x32_f16 v[116:119], v[184:187], v[208:211], v[116:119]
	v_mfma_f32_16x16x32_f16 v[108:111], v[176:179], v[216:219], v[108:111]
	v_mfma_f32_16x16x32_f16 v[104:107], v[184:187], v[216:219], v[104:107]
	v_mfma_f32_16x16x32_f16 v[92:95], v[176:179], v[228:231], v[92:95]
	v_mfma_f32_16x16x32_f16 v[88:91], v[184:187], v[228:231], v[88:91]
	v_mfma_f32_16x16x32_f16 v[76:79], v[176:179], v[236:239], v[76:79]
	v_mfma_f32_16x16x32_f16 v[72:75], v[184:187], v[236:239], v[72:75]
	v_mfma_f32_16x16x32_f16 v[120:123], v[188:191], v[204:207], v[120:123]
	v_mfma_f32_16x16x32_f16 v[112:115], v[196:199], v[204:207], v[112:115]
	v_mfma_f32_16x16x32_f16 v[100:103], v[188:191], v[212:215], v[100:103]
	v_mfma_f32_16x16x32_f16 v[96:99], v[196:199], v[212:215], v[96:99]
	v_mfma_f32_16x16x32_f16 v[84:87], v[188:191], v[220:223], v[84:87]
	v_mfma_f32_16x16x32_f16 v[80:83], v[196:199], v[220:223], v[80:83]
	v_mfma_f32_16x16x32_f16 v[68:71], v[188:191], v[232:235], v[68:71]
	v_mfma_f32_16x16x32_f16 v[64:67], v[196:199], v[232:235], v[64:67]
	v_mfma_f32_16x16x32_f16 v[120:123], v[192:195], v[208:211], v[120:123]
	v_mfma_f32_16x16x32_f16 v[112:115], v[200:203], v[208:211], v[112:115]
	v_mfma_f32_16x16x32_f16 v[100:103], v[192:195], v[216:219], v[100:103]
	v_mfma_f32_16x16x32_f16 v[96:99], v[200:203], v[216:219], v[96:99]
	v_mfma_f32_16x16x32_f16 v[84:87], v[192:195], v[228:231], v[84:87]
	v_mfma_f32_16x16x32_f16 v[80:83], v[200:203], v[228:231], v[80:83]
	v_mfma_f32_16x16x32_f16 v[68:71], v[192:195], v[236:239], v[68:71]
	v_mfma_f32_16x16x32_f16 v[64:67], v[200:203], v[236:239], v[64:67]
	s_barrier
	s_mov_b32 m0, s45
	v_lshl_add_u64 v[148:149], v[148:149], 0, s[16:17]
	s_add_u32 s12, s12, 0x40080
	ds_read_b128 v[204:207], v153 offset:49152
	ds_read_b128 v[208:211], v153 offset:50176
	ds_read_b128 v[212:215], v153 offset:51200
	ds_read_b128 v[216:219], v153 offset:52224
	ds_read_b128 v[220:223], v153 offset:53248
	ds_read_b128 v[228:231], v153 offset:54272
	ds_read_b128 v[232:235], v153 offset:55296
	ds_read_b128 v[236:239], v153 offset:56320
	global_load_lds_dwordx4 v[148:149], off
	v_lshl_add_u64 v[148:149], v[224:225], 0, s[16:17]
	s_mov_b32 m0, s49
	s_addc_u32 s13, s13, 0
	global_load_lds_dwordx4 v[148:149], off
	v_lshl_add_u64 v[148:149], s[12:13], 0, v[132:133]
	s_mov_b32 m0, s62
	s_nop 0
	global_load_lds_dwordx4 v[148:149], off
	v_lshl_add_u64 v[148:149], s[12:13], 0, v[128:129]
	s_mov_b32 m0, s63
	s_nop 0
	global_load_lds_dwordx4 v[148:149], off
	v_lshl_add_u64 v[148:149], v[240:241], 0, s[16:17]
	s_mov_b32 m0, s60
	s_nop 0
	global_load_lds_dwordx4 v[148:149], off
	v_lshl_add_u64 v[148:149], v[242:243], 0, s[16:17]
	s_mov_b32 m0, s61
	s_nop 0
	global_load_lds_dwordx4 v[148:149], off
	s_waitcnt vmcnt(8)
	s_waitcnt lgkmcnt(0)
	s_barrier
	s_waitcnt lgkmcnt(0)
	v_mfma_f32_16x16x32_f16 v[60:63], v[172:175], v[204:207], v[60:63]
	v_mfma_f32_16x16x32_f16 v[56:59], v[180:183], v[204:207], v[56:59]
	v_mfma_f32_16x16x32_f16 v[44:47], v[172:175], v[212:215], v[44:47]
	v_mfma_f32_16x16x32_f16 v[40:43], v[180:183], v[212:215], v[40:43]
	v_mfma_f32_16x16x32_f16 v[28:31], v[172:175], v[220:223], v[28:31]
	v_mfma_f32_16x16x32_f16 v[24:27], v[180:183], v[220:223], v[24:27]
	v_mfma_f32_16x16x32_f16 v[12:15], v[172:175], v[232:235], v[12:15]
	v_mfma_f32_16x16x32_f16 v[8:11], v[180:183], v[232:235], v[8:11]
	v_mfma_f32_16x16x32_f16 v[60:63], v[176:179], v[208:211], v[60:63]
	v_mfma_f32_16x16x32_f16 v[56:59], v[184:187], v[208:211], v[56:59]
	v_mfma_f32_16x16x32_f16 v[44:47], v[176:179], v[216:219], v[44:47]
	v_mfma_f32_16x16x32_f16 v[40:43], v[184:187], v[216:219], v[40:43]
	v_mfma_f32_16x16x32_f16 v[28:31], v[176:179], v[228:231], v[28:31]
	v_mfma_f32_16x16x32_f16 v[24:27], v[184:187], v[228:231], v[24:27]
	v_mfma_f32_16x16x32_f16 v[12:15], v[176:179], v[236:239], v[12:15]
	v_mfma_f32_16x16x32_f16 v[8:11], v[184:187], v[236:239], v[8:11]
	v_mfma_f32_16x16x32_f16 v[52:55], v[188:191], v[204:207], v[52:55]
	v_mfma_f32_16x16x32_f16 v[48:51], v[196:199], v[204:207], v[48:51]
	v_mfma_f32_16x16x32_f16 v[36:39], v[188:191], v[212:215], v[36:39]
	v_mfma_f32_16x16x32_f16 v[32:35], v[196:199], v[212:215], v[32:35]
	v_mfma_f32_16x16x32_f16 v[20:23], v[188:191], v[220:223], v[20:23]
	v_mfma_f32_16x16x32_f16 v[16:19], v[196:199], v[220:223], v[16:19]
	v_mfma_f32_16x16x32_f16 v[4:7], v[188:191], v[232:235], v[4:7]
	v_mfma_f32_16x16x32_f16 v[0:3], v[196:199], v[232:235], v[0:3]
	v_mfma_f32_16x16x32_f16 v[52:55], v[192:195], v[208:211], v[52:55]
	v_mfma_f32_16x16x32_f16 v[48:51], v[200:203], v[208:211], v[48:51]
	v_mfma_f32_16x16x32_f16 v[36:39], v[192:195], v[216:219], v[36:39]
	v_mfma_f32_16x16x32_f16 v[32:35], v[200:203], v[216:219], v[32:35]
	v_mfma_f32_16x16x32_f16 v[20:23], v[192:195], v[228:231], v[20:23]
	v_mfma_f32_16x16x32_f16 v[16:19], v[200:203], v[228:231], v[16:19]
	v_mfma_f32_16x16x32_f16 v[4:7], v[192:195], v[236:239], v[4:7]
	v_mfma_f32_16x16x32_f16 v[0:3], v[200:203], v[236:239], v[0:3]
	s_barrier
	s_add_i32 s74, s74, 2
	s_add_u32 s10, s10, 0x100
	s_addc_u32 s11, s11, 0
	s_add_u32 s72, s72, 0x100
	s_addc_u32 s73, s73, 0
	s_cmp_gt_u32 s74, 13

; #define PG8_STAGE(bufoff, gbase, voff) do { _Pragma("unroll") for (int _i = 0; _i < 2; ++_i) \
;         __builtin_amdgcn_global_load_lds((const unsigned*)((const char*)(gbase) + (voff)[_i]), (PG8_LAS unsigned*)(lds + (bufoff) + ldsw + _i * 8192), 16, 0, 0); } while (0)
; #define PG8_LDA(dst, b, h) do { _Pragma("unroll") for (int m = 0; m < 4; ++m) _Pragma("unroll") for (int k = 0; k < 2; ++k) dst[m][k] = *(const PG8_LAS bf16x8*)(lds + PG8_SA(b, h) + aoff + m * 2048 + k * 1024); } while (0)
; #define PG8_MMA(ai, bj, At, Bt) do { __builtin_amdgcn_s_setprio(1); _Pragma("unroll") for (int m = 0; m < 4; ++m) _Pragma("unroll") for (int n = 0; n < 2; ++n) _Pragma("unroll") for (int k = 0; k < 2; ++k) \
;         acc[ai][bj][m][n] = mma16<F16>(Bt[n][k], At[m][k], acc[ai][bj][m][n]); __builtin_amdgcn_s_setprio(0); } while (0)
; #define PG8_WAIT_V(n) asm volatile("s_waitcnt vmcnt(" #n ")" ::: "memory")
; #define PG8_WAIT_L(n) asm volatile("s_waitcnt lgkmcnt(" #n ")" ::: "memory")
; #define PG8_BAR __builtin_amdgcn_s_barrier()
; #define PG8_SCHED __builtin_amdgcn_sched_barrier(0)
; template <class Epi, class Sched, bool ALIGN_EPI = false, bool SP2 = false, bool F16 = false, bool TOKPERM = false>
; __device__ __forceinline__ void gemm_phase(PG8_LAS unsigned char* lds, const Gemm g, const Sched& S, const Epi& E, int wv) {
;     ...
;             PG8_WAIT_V(8); PG8_WAIT_L(0); PG8_BAR; PG8_MMA(0, 0, At, B0); PG8_MMA(0, 1, At, B1); PG8_BAR; PG8_SCHED;
;             PG8_LDA(At, 0, 1); PG8_STAGE(PG8_SB(0, 0), b2, voffB); PG8_STAGE(PG8_SB(0, 1), b2 + hstep, voffB); PG8_STAGE(PG8_SA(0, 0), a2, voffA);
;             PG8_WAIT_V(8); PG8_WAIT_L(0); PG8_BAR; PG8_MMA(1, 0, At, B0); PG8_MMA(1, 1, At, B1); PG8_BAR; PG8_SCHED;
.Lvmw_950_0:
	s_waitcnt lgkmcnt(0)
	s_barrier
	s_waitcnt lgkmcnt(0)
	v_mfma_f32_16x16x32_f16 v[124:127], v[172:175], v[204:207], 0
	v_mfma_f32_16x16x32_f16 v[116:119], v[180:183], v[204:207], 0
	v_mfma_f32_16x16x32_f16 v[108:111], v[172:175], v[212:215], 0
	v_mfma_f32_16x16x32_f16 v[104:107], v[180:183], v[212:215], 0
	v_mfma_f32_16x16x32_f16 v[92:95], v[172:175], v[220:223], 0
	v_mfma_f32_16x16x32_f16 v[88:91], v[180:183], v[220:223], 0
	v_mfma_f32_16x16x32_f16 v[76:79], v[172:175], v[232:235], 0
	v_mfma_f32_16x16x32_f16 v[72:75], v[180:183], v[232:235], 0
	v_mfma_f32_16x16x32_f16 v[124:127], v[176:179], v[208:211], v[124:127]
	v_mfma_f32_16x16x32_f16 v[116:119], v[184:187], v[208:211], v[116:119]
	v_mfma_f32_16x16x32_f16 v[108:111], v[176:179], v[216:219], v[108:111]
	v_mfma_f32_16x16x32_f16 v[104:107], v[184:187], v[216:219], v[104:107]
	v_mfma_f32_16x16x32_f16 v[92:95], v[176:179], v[228:231], v[92:95]
	v_mfma_f32_16x16x32_f16 v[88:91], v[184:187], v[228:231], v[88:91]
	v_mfma_f32_16x16x32_f16 v[76:79], v[176:179], v[236:239], v[76:79]
	v_mfma_f32_16x16x32_f16 v[72:75], v[184:187], v[236:239], v[72:75]
	v_mfma_f32_16x16x32_f16 v[120:123], v[188:191], v[204:207], 0
	v_mfma_f32_16x16x32_f16 v[112:115], v[196:199], v[204:207], 0
	v_mfma_f32_16x16x32_f16 v[100:103], v[188:191], v[212:215], 0
	v_mfma_f32_16x16x32_f16 v[96:99], v[196:199], v[212:215], 0
	v_mfma_f32_16x16x32_f16 v[84:87], v[188:191], v[220:223], 0
	v_mfma_f32_16x16x32_f16 v[80:83], v[196:199], v[220:223], 0
	v_mfma_f32_16x16x32_f16 v[68:71], v[188:191], v[232:235], 0
	v_mfma_f32_16x16x32_f16 v[64:67], v[196:199], v[232:235], 0
	v_mfma_f32_16x16x32_f16 v[120:123], v[192:195], v[208:211], v[120:123]
	v_mfma_f32_16x16x32_f16 v[112:115], v[200:203], v[208:211], v[112:115]
	v_mfma_f32_16x16x32_f16 v[100:103], v[192:195], v[216:219], v[100:103]
	v_mfma_f32_16x16x32_f16 v[96:99], v[200:203], v[216:219], v[96:99]
	v_mfma_f32_16x16x32_f16 v[84:87], v[192:195], v[228:231], v[84:87]
	v_mfma_f32_16x16x32_f16 v[80:83], v[200:203], v[228:231], v[80:83]
	v_mfma_f32_16x16x32_f16 v[68:71], v[192:195], v[236:239], v[68:71]
	v_mfma_f32_16x16x32_f16 v[64:67], v[200:203], v[236:239], v[64:67]
	s_barrier
	s_mov_b32 m0, s5
	v_lshl_add_u64 v[148:149], s[12:13], 0, v[132:133]
	s_add_u32 s76, s12, 0x40000
	ds_read_b128 v[204:207], v153 offset:16384
	ds_read_b128 v[208:211], v153 offset:17408
	ds_read_b128 v[212:215], v153 offset:18432
	ds_read_b128 v[216:219], v153 offset:19456
	ds_read_b128 v[220:223], v153 offset:20480
	ds_read_b128 v[228:231], v153 offset:21504
	ds_read_b128 v[232:235], v153 offset:22528
	ds_read_b128 v[236:239], v153 offset:23552
	global_load_lds_dwordx4 v[148:149], off
	v_lshl_add_u64 v[224:225], s[12:13], 0, v[128:129]
	s_mov_b32 m0, s21
	s_addc_u32 s77, s13, 0
	global_load_lds_dwordx4 v[224:225], off
	v_lshl_add_u64 v[240:241], s[76:77], 0, v[132:133]
	s_mov_b32 m0, s23
	v_lshl_add_u64 v[242:243], s[56:57], 0, v[130:131]
	global_load_lds_dwordx4 v[240:241], off
	v_lshl_add_u64 v[240:241], s[76:77], 0, v[128:129]
	s_mov_b32 m0, s33
	s_nop 0
	global_load_lds_dwordx4 v[240:241], off
	v_lshl_add_u64 v[240:241], s[56:57], 0, v[134:135]
	s_mov_b32 m0, s2
	s_nop 0
	global_load_lds_dwordx4 v[240:241], off
	s_mov_b32 m0, s36
	s_nop 0
	global_load_lds_dwordx4 v[242:243], off
	s_waitcnt vmcnt(16)
	s_cmp_lg_u32 s99, -1
	s_cbranch_scc1 .Lvmw_950_1
	s_waitcnt vmcnt(8)
.Lvmw_950_1:
	s_waitcnt lgkmcnt(0)
	s_barrier
	s_waitcnt lgkmcnt(0)
	v_mfma_f32_16x16x32_f16 v[60:63], v[172:175], v[204:207], 0
	v_mfma_f32_16x16x32_f16 v[56:59], v[180:183], v[204:207], 0
	v_mfma_f32_16x16x32_f16 v[44:47], v[172:175], v[212:215], 0
	v_mfma_f32_16x16x32_f16 v[40:43], v[180:183], v[212:215], 0
	v_mfma_f32_16x16x32_f16 v[28:31], v[172:175], v[220:223], 0
	v_mfma_f32_16x16x32_f16 v[24:27], v[180:183], v[220:223], 0
	v_mfma_f32_16x16x32_f16 v[12:15], v[172:175], v[232:235], 0
	v_mfma_f32_16x16x32_f16 v[8:11], v[180:183], v[232:235], 0
	v_mfma_f32_16x16x32_f16 v[60:63], v[176:179], v[208:211], v[60:63]
	v_mfma_f32_16x16x32_f16 v[56:59], v[184:187], v[208:211], v[56:59]
	v_mfma_f32_16x16x32_f16 v[44:47], v[176:179], v[216:219], v[44:47]
	v_mfma_f32_16x16x32_f16 v[40:43], v[184:187], v[216:219], v[40:43]
	v_mfma_f32_16x16x32_f16 v[28:31], v[176:179], v[228:231], v[28:31]
	v_mfma_f32_16x16x32_f16 v[24:27], v[184:187], v[228:231], v[24:27]
	v_mfma_f32_16x16x32_f16 v[12:15], v[176:179], v[236:239], v[12:15]
	v_mfma_f32_16x16x32_f16 v[8:11], v[184:187], v[236:239], v[8:11]
	v_mfma_f32_16x16x32_f16 v[52:55], v[188:191], v[204:207], 0
	v_mfma_f32_16x16x32_f16 v[48:51], v[196:199], v[204:207], 0
	v_mfma_f32_16x16x32_f16 v[36:39], v[188:191], v[212:215], 0
	v_mfma_f32_16x16x32_f16 v[32:35], v[196:199], v[212:215], 0
	v_mfma_f32_16x16x32_f16 v[20:23], v[188:191], v[220:223], 0
	v_mfma_f32_16x16x32_f16 v[16:19], v[196:199], v[220:223], 0
	v_mfma_f32_16x16x32_f16 v[4:7], v[188:191], v[232:235], 0
	v_mfma_f32_16x16x32_f16 v[0:3], v[196:199], v[232:235], 0
	v_mfma_f32_16x16x32_f16 v[52:55], v[192:195], v[208:211], v[52:55]
	v_mfma_f32_16x16x32_f16 v[48:51], v[200:203], v[208:211], v[48:51]
	v_mfma_f32_16x16x32_f16 v[36:39], v[192:195], v[216:219], v[36:39]
	v_mfma_f32_16x16x32_f16 v[32:35], v[200:203], v[216:219], v[32:35]
	v_mfma_f32_16x16x32_f16 v[20:23], v[192:195], v[228:231], v[20:23]
	v_mfma_f32_16x16x32_f16 v[16:19], v[200:203], v[228:231], v[16:19]
	v_mfma_f32_16x16x32_f16 v[4:7], v[192:195], v[236:239], v[4:7]
	v_mfma_f32_16x16x32_f16 v[0:3], v[200:203], v[236:239], v[0:3]
	s_barrier
; #define PG8_STAGE(bufoff, gbase, voff) do { _Pragma("unroll") for (int _i = 0; _i < 2; ++_i) \
;         __builtin_amdgcn_global_load_lds((const unsigned*)((const char*)(gbase) + (voff)[_i]), (PG8_LAS unsigned*)(lds + (bufoff) + ldsw + _i * 8192), 16, 0, 0); } while (0)
; #define PG8_LDA(dst, b, h) do { _Pragma("unroll") for (int m = 0; m < 4; ++m) _Pragma("unroll") for (int k = 0; k < 2; ++k) dst[m][k] = *(const PG8_LAS bf16x8*)(lds + PG8_SA(b, h) + aoff + m * 2048 + k * 1024); } while (0)
; #define PG8_LDB(dst, b, h) do { _Pragma("unroll") for (int n = 0; n < 2; ++n) _Pragma("unroll") for (int k = 0; k < 2; ++k) dst[n][k] = *(const PG8_LAS bf16x8*)(lds + PG8_SB(b, h) + boff + n * 2048 + k * 1024); } while (0)
; #define PG8_MMA(ai, bj, At, Bt) do { __builtin_amdgcn_s_setprio(1); _Pragma("unroll") for (int m = 0; m < 4; ++m) _Pragma("unroll") for (int n = 0; n < 2; ++n) _Pragma("unroll") for (int k = 0; k < 2; ++k) \
;         acc[ai][bj][m][n] = mma16<F16>(Bt[n][k], At[m][k], acc[ai][bj][m][n]); __builtin_amdgcn_s_setprio(0); } while (0)
; #define PG8_WAIT_V(n) asm volatile("s_waitcnt vmcnt(" #n ")" ::: "memory")
; #define PG8_WAIT_L(n) asm volatile("s_waitcnt lgkmcnt(" #n ")" ::: "memory")
; #define PG8_BAR __builtin_amdgcn_s_barrier()
; #define PG8_SCHED __builtin_amdgcn_sched_barrier(0)
; template <class Epi, class Sched, bool ALIGN_EPI = false, bool SP2 = false, bool F16 = false, bool TOKPERM = false>
; __device__ __forceinline__ void gemm_phase(PG8_LAS unsigned char* lds, const Gemm g, const Sched& S, const Epi& E, int wv) {
;     ...
;         for (int t = 0; t < nt; t += 2) {
;     ...
;             PG8_LDB(B0, 1, 0); PG8_LDB(B1, 1, 1); PG8_SCHED; PG8_LDA(At, 1, 0); PG8_STAGE(PG8_SA(0, 1), a2 + hstep, voffA);
;             PG8_WAIT_V(8); PG8_WAIT_L(0); PG8_BAR; PG8_MMA(0, 0, At, B0); PG8_MMA(0, 1, At, B1); PG8_BAR; PG8_SCHED;
;             PG8_LDA(At, 1, 1); PG8_STAGE(PG8_SB(1, 0), b3, voffB); PG8_STAGE(PG8_SB(1, 1), b3 + hstep, voffB); PG8_STAGE(PG8_SA(1, 0), a3, voffA);
;             PG8_WAIT_V(8); PG8_WAIT_L(0); PG8_BAR; PG8_MMA(1, 0, At, B0); PG8_MMA(1, 1, At, B1); PG8_BAR; PG8_SCHED;
	ds_read_b128 v[172:175], v163
	ds_read_b128 v[176:179], v164
	ds_read_b128 v[180:183], v165
	ds_read_b128 v[184:187], v166
	ds_read_b128 v[188:191], v167
	ds_read_b128 v[192:195], v168
	ds_read_b128 v[196:199], v169
	ds_read_b128 v[200:203], v170
	s_add_u32 s56, s56, 0x40000
	s_addc_u32 s57, s57, 0
	s_mov_b32 m0, s37
	v_lshl_add_u64 v[244:245], s[56:57], 0, v[134:135]
	ds_read_b128 v[204:207], v153 offset:32768
	ds_read_b128 v[208:211], v153 offset:33792
	ds_read_b128 v[212:215], v153 offset:34816
	ds_read_b128 v[216:219], v153 offset:35840
	ds_read_b128 v[220:223], v153 offset:36864
	ds_read_b128 v[228:231], v153 offset:37888
	ds_read_b128 v[232:235], v153 offset:38912
	ds_read_b128 v[236:239], v153 offset:39936
	global_load_lds_dwordx4 v[244:245], off
	v_lshl_add_u64 v[244:245], s[56:57], 0, v[130:131]
	s_mov_b32 m0, s44
	s_nop 0
	global_load_lds_dwordx4 v[244:245], off
	s_waitcnt vmcnt(8)
	s_waitcnt lgkmcnt(0)
	s_barrier
	s_waitcnt lgkmcnt(0)
	v_mfma_f32_16x16x32_f16 v[124:127], v[172:175], v[204:207], v[124:127]
	v_mfma_f32_16x16x32_f16 v[116:119], v[180:183], v[204:207], v[116:119]
	v_mfma_f32_16x16x32_f16 v[108:111], v[172:175], v[212:215], v[108:111]
	v_mfma_f32_16x16x32_f16 v[104:107], v[180:183], v[212:215], v[104:107]
	v_mfma_f32_16x16x32_f16 v[92:95], v[172:175], v[220:223], v[92:95]
	v_mfma_f32_16x16x32_f16 v[88:91], v[180:183], v[220:223], v[88:91]
	v_mfma_f32_16x16x32_f16 v[76:79], v[172:175], v[232:235], v[76:79]
	v_mfma_f32_16x16x32_f16 v[72:75], v[180:183], v[232:235], v[72:75]
	v_mfma_f32_16x16x32_f16 v[124:127], v[176:179], v[208:211], v[124:127]
	v_mfma_f32_16x16x32_f16 v[116:119], v[184:187], v[208:211], v[116:119]
	v_mfma_f32_16x16x32_f16 v[108:111], v[176:179], v[216:219], v[108:111]
	v_mfma_f32_16x16x32_f16 v[104:107], v[184:187], v[216:219], v[104:107]
	v_mfma_f32_16x16x32_f16 v[92:95], v[176:179], v[228:231], v[92:95]
	v_mfma_f32_16x16x32_f16 v[88:91], v[184:187], v[228:231], v[88:91]
	v_mfma_f32_16x16x32_f16 v[76:79], v[176:179], v[236:239], v[76:79]
	v_mfma_f32_16x16x32_f16 v[72:75], v[184:187], v[236:239], v[72:75]
	v_mfma_f32_16x16x32_f16 v[120:123], v[188:191], v[204:207], v[120:123]
	v_mfma_f32_16x16x32_f16 v[112:115], v[196:199], v[204:207], v[112:115]
	v_mfma_f32_16x16x32_f16 v[100:103], v[188:191], v[212:215], v[100:103]
	v_mfma_f32_16x16x32_f16 v[96:99], v[196:199], v[212:215], v[96:99]
	v_mfma_f32_16x16x32_f16 v[84:87], v[188:191], v[220:223], v[84:87]
	v_mfma_f32_16x16x32_f16 v[80:83], v[196:199], v[220:223], v[80:83]
	v_mfma_f32_16x16x32_f16 v[68:71], v[188:191], v[232:235], v[68:71]
	v_mfma_f32_16x16x32_f16 v[64:67], v[196:199], v[232:235], v[64:67]
	v_mfma_f32_16x16x32_f16 v[120:123], v[192:195], v[208:211], v[120:123]
	v_mfma_f32_16x16x32_f16 v[112:115], v[200:203], v[208:211], v[112:115]
	v_mfma_f32_16x16x32_f16 v[100:103], v[192:195], v[216:219], v[100:103]
	v_mfma_f32_16x16x32_f16 v[96:99], v[200:203], v[216:219], v[96:99]
	v_mfma_f32_16x16x32_f16 v[84:87], v[192:195], v[228:231], v[84:87]
	v_mfma_f32_16x16x32_f16 v[80:83], v[200:203], v[228:231], v[80:83]
	v_mfma_f32_16x16x32_f16 v[68:71], v[192:195], v[236:239], v[68:71]
	v_mfma_f32_16x16x32_f16 v[64:67], v[200:203], v[236:239], v[64:67]
	s_barrier
	s_mov_b32 m0, s58
	v_lshl_add_u64 v[148:149], v[148:149], 0, s[16:17]
	s_add_u32 s12, s12, 0x40080
	ds_read_b128 v[204:207], v153 offset:49152
	ds_read_b128 v[208:211], v153 offset:50176
	ds_read_b128 v[212:215], v153 offset:51200
	ds_read_b128 v[216:219], v153 offset:52224
	ds_read_b128 v[220:223], v153 offset:53248
	ds_read_b128 v[228:231], v153 offset:54272
	ds_read_b128 v[232:235], v153 offset:55296
	ds_read_b128 v[236:239], v153 offset:56320
	global_load_lds_dwordx4 v[148:149], off
	v_lshl_add_u64 v[148:149], v[224:225], 0, s[16:17]
	s_mov_b32 m0, s59
	s_addc_u32 s13, s13, 0
	global_load_lds_dwordx4 v[148:149], off
	v_lshl_add_u64 v[148:149], s[12:13], 0, v[132:133]
	s_mov_b32 m0, s62
	s_nop 0
	global_load_lds_dwordx4 v[148:149], off
	v_lshl_add_u64 v[148:149], s[12:13], 0, v[128:129]
	s_mov_b32 m0, s63
	s_nop 0
	global_load_lds_dwordx4 v[148:149], off
	v_lshl_add_u64 v[148:149], v[240:241], 0, s[16:17]
	s_mov_b32 m0, s60
	s_nop 0
	global_load_lds_dwordx4 v[148:149], off
	v_lshl_add_u64 v[148:149], v[242:243], 0, s[16:17]
	s_mov_b32 m0, s61
	s_nop 0
	global_load_lds_dwordx4 v[148:149], off
	s_waitcnt vmcnt(8)
	s_waitcnt lgkmcnt(0)
	s_barrier
	s_waitcnt lgkmcnt(0)
	v_mfma_f32_16x16x32_f16 v[60:63], v[172:175], v[204:207], v[60:63]
	v_mfma_f32_16x16x32_f16 v[56:59], v[180:183], v[204:207], v[56:59]
	v_mfma_f32_16x16x32_f16 v[44:47], v[172:175], v[212:215], v[44:47]
	v_mfma_f32_16x16x32_f16 v[40:43], v[180:183], v[212:215], v[40:43]
	v_mfma_f32_16x16x32_f16 v[28:31], v[172:175], v[220:223], v[28:31]
	v_mfma_f32_16x16x32_f16 v[24:27], v[180:183], v[220:223], v[24:27]
	v_mfma_f32_16x16x32_f16 v[12:15], v[172:175], v[232:235], v[12:15]
	v_mfma_f32_16x16x32_f16 v[8:11], v[180:183], v[232:235], v[8:11]
	v_mfma_f32_16x16x32_f16 v[60:63], v[176:179], v[208:211], v[60:63]
	v_mfma_f32_16x16x32_f16 v[56:59], v[184:187], v[208:211], v[56:59]
	v_mfma_f32_16x16x32_f16 v[44:47], v[176:179], v[216:219], v[44:47]
	v_mfma_f32_16x16x32_f16 v[40:43], v[184:187], v[216:219], v[40:43]
	v_mfma_f32_16x16x32_f16 v[28:31], v[176:179], v[228:231], v[28:31]
	v_mfma_f32_16x16x32_f16 v[24:27], v[184:187], v[228:231], v[24:27]
	v_mfma_f32_16x16x32_f16 v[12:15], v[176:179], v[236:239], v[12:15]
	v_mfma_f32_16x16x32_f16 v[8:11], v[184:187], v[236:239], v[8:11]
	v_mfma_f32_16x16x32_f16 v[52:55], v[188:191], v[204:207], v[52:55]
	v_mfma_f32_16x16x32_f16 v[48:51], v[196:199], v[204:207], v[48:51]
	v_mfma_f32_16x16x32_f16 v[36:39], v[188:191], v[212:215], v[36:39]
	v_mfma_f32_16x16x32_f16 v[32:35], v[196:199], v[212:215], v[32:35]
	v_mfma_f32_16x16x32_f16 v[20:23], v[188:191], v[220:223], v[20:23]
	v_mfma_f32_16x16x32_f16 v[16:19], v[196:199], v[220:223], v[16:19]
	v_mfma_f32_16x16x32_f16 v[4:7], v[188:191], v[232:235], v[4:7]
	v_mfma_f32_16x16x32_f16 v[0:3], v[196:199], v[232:235], v[0:3]
	v_mfma_f32_16x16x32_f16 v[52:55], v[192:195], v[208:211], v[52:55]
	v_mfma_f32_16x16x32_f16 v[48:51], v[200:203], v[208:211], v[48:51]
	v_mfma_f32_16x16x32_f16 v[36:39], v[192:195], v[216:219], v[36:39]
	v_mfma_f32_16x16x32_f16 v[32:35], v[200:203], v[216:219], v[32:35]
	v_mfma_f32_16x16x32_f16 v[20:23], v[192:195], v[228:231], v[20:23]
	v_mfma_f32_16x16x32_f16 v[16:19], v[200:203], v[228:231], v[16:19]
	v_mfma_f32_16x16x32_f16 v[4:7], v[192:195], v[236:239], v[4:7]
	v_mfma_f32_16x16x32_f16 v[0:3], v[200:203], v[236:239], v[0:3]
	s_barrier
	s_add_i32 s74, s74, 2
	s_add_u32 s10, s10, 0x100
	s_addc_u32 s11, s11, 0
	s_add_u32 s72, s72, 0x100
	s_addc_u32 s73, s73, 0
	s_cmp_gt_u32 s74, 13

; #define PG8_STAGE(bufoff, gbase, voff) do { _Pragma("unroll") for (int _i = 0; _i < 2; ++_i) \
;         __builtin_amdgcn_global_load_lds((const unsigned*)((const char*)(gbase) + (voff)[_i]), (PG8_LAS unsigned*)(lds + (bufoff) + ldsw + _i * 8192), 16, 0, 0); } while (0)
; #define PG8_LDA(dst, b, h) do { _Pragma("unroll") for (int m = 0; m < 4; ++m) _Pragma("unroll") for (int k = 0; k < 2; ++k) dst[m][k] = *(const PG8_LAS bf16x8*)(lds + PG8_SA(b, h) + aoff + m * 2048 + k * 1024); } while (0)
; #define PG8_MMA(ai, bj, At, Bt) do { __builtin_amdgcn_s_setprio(1); _Pragma("unroll") for (int m = 0; m < 4; ++m) _Pragma("unroll") for (int n = 0; n < 2; ++n) _Pragma("unroll") for (int k = 0; k < 2; ++k) \
;         acc[ai][bj][m][n] = mma16<F16>(Bt[n][k], At[m][k], acc[ai][bj][m][n]); __builtin_amdgcn_s_setprio(0); } while (0)
; #define PG8_WAIT_V(n) asm volatile("s_waitcnt vmcnt(" #n ")" ::: "memory")
; #define PG8_WAIT_L(n) asm volatile("s_waitcnt lgkmcnt(" #n ")" ::: "memory")
; #define PG8_BAR __builtin_amdgcn_s_barrier()
; #define PG8_SCHED __builtin_amdgcn_sched_barrier(0)
; template <class Epi, class Sched, bool ALIGN_EPI = false, bool SP2 = false, bool F16 = false, bool TOKPERM = false>
; __device__ __forceinline__ void gemm_phase(PG8_LAS unsigned char* lds, const Gemm g, const Sched& S, const Epi& E, int wv) {
;     ...
;             PG8_WAIT_V(8); PG8_WAIT_L(0); PG8_BAR; PG8_MMA(0, 0, At, B0); PG8_MMA(0, 1, At, B1); PG8_BAR; PG8_SCHED;
;             PG8_LDA(At, 0, 1); PG8_STAGE(PG8_SB(0, 0), b2, voffB); PG8_STAGE(PG8_SB(0, 1), b2 + hstep, voffB); PG8_STAGE(PG8_SA(0, 0), a2, voffA);
;             PG8_WAIT_V(8); PG8_WAIT_L(0); PG8_BAR; PG8_MMA(1, 0, At, B0); PG8_MMA(1, 1, At, B1); PG8_BAR; PG8_SCHED;
.Lvmw_1607_0:
	s_waitcnt lgkmcnt(0)
	s_barrier
	s_waitcnt lgkmcnt(0)
	v_mfma_f32_16x16x32_f16 v[124:127], v[172:175], v[204:207], 0
	v_mfma_f32_16x16x32_f16 v[116:119], v[180:183], v[204:207], 0
	v_mfma_f32_16x16x32_f16 v[108:111], v[172:175], v[212:215], 0
	v_mfma_f32_16x16x32_f16 v[104:107], v[180:183], v[212:215], 0
	v_mfma_f32_16x16x32_f16 v[92:95], v[172:175], v[220:223], 0
	v_mfma_f32_16x16x32_f16 v[88:91], v[180:183], v[220:223], 0
	v_mfma_f32_16x16x32_f16 v[76:79], v[172:175], v[228:231], 0
	v_mfma_f32_16x16x32_f16 v[72:75], v[180:183], v[228:231], 0
	v_mfma_f32_16x16x32_f16 v[124:127], v[176:179], v[208:211], v[124:127]
	v_mfma_f32_16x16x32_f16 v[116:119], v[184:187], v[208:211], v[116:119]
	v_mfma_f32_16x16x32_f16 v[108:111], v[176:179], v[216:219], v[108:111]
	v_mfma_f32_16x16x32_f16 v[104:107], v[184:187], v[216:219], v[104:107]
	v_mfma_f32_16x16x32_f16 v[92:95], v[176:179], v[224:227], v[92:95]
	v_mfma_f32_16x16x32_f16 v[88:91], v[184:187], v[224:227], v[88:91]
	v_mfma_f32_16x16x32_f16 v[76:79], v[176:179], v[232:235], v[76:79]
	v_mfma_f32_16x16x32_f16 v[72:75], v[184:187], v[232:235], v[72:75]
	v_mfma_f32_16x16x32_f16 v[120:123], v[188:191], v[204:207], 0
	v_mfma_f32_16x16x32_f16 v[112:115], v[196:199], v[204:207], 0
	v_mfma_f32_16x16x32_f16 v[100:103], v[188:191], v[212:215], 0
	v_mfma_f32_16x16x32_f16 v[96:99], v[196:199], v[212:215], 0
	v_mfma_f32_16x16x32_f16 v[84:87], v[188:191], v[220:223], 0
	v_mfma_f32_16x16x32_f16 v[80:83], v[196:199], v[220:223], 0
	v_mfma_f32_16x16x32_f16 v[68:71], v[188:191], v[228:231], 0
	v_mfma_f32_16x16x32_f16 v[64:67], v[196:199], v[228:231], 0
	v_mfma_f32_16x16x32_f16 v[120:123], v[192:195], v[208:211], v[120:123]
	v_mfma_f32_16x16x32_f16 v[112:115], v[200:203], v[208:211], v[112:115]
	v_mfma_f32_16x16x32_f16 v[100:103], v[192:195], v[216:219], v[100:103]
	v_mfma_f32_16x16x32_f16 v[96:99], v[200:203], v[216:219], v[96:99]
	v_mfma_f32_16x16x32_f16 v[84:87], v[192:195], v[224:227], v[84:87]
	v_mfma_f32_16x16x32_f16 v[80:83], v[200:203], v[224:227], v[80:83]
	v_mfma_f32_16x16x32_f16 v[68:71], v[192:195], v[232:235], v[68:71]
	v_mfma_f32_16x16x32_f16 v[64:67], v[200:203], v[232:235], v[64:67]
	s_barrier
	s_mov_b32 m0, s21
	v_lshl_add_u64 v[148:149], s[10:11], 0, v[132:133]
	s_add_u32 s70, s10, 0x40000
	ds_read_b128 v[204:207], v153 offset:16384
	ds_read_b128 v[208:211], v153 offset:17408
	ds_read_b128 v[212:215], v153 offset:18432
	ds_read_b128 v[216:219], v153 offset:19456
	ds_read_b128 v[220:223], v153 offset:20480
	ds_read_b128 v[224:227], v153 offset:21504
	ds_read_b128 v[228:231], v153 offset:22528
	ds_read_b128 v[232:235], v153 offset:23552
	global_load_lds_dwordx4 v[148:149], off
	v_lshl_add_u64 v[236:237], s[10:11], 0, v[128:129]
	s_mov_b32 m0, s33
	s_addc_u32 s71, s11, 0
	global_load_lds_dwordx4 v[236:237], off
	v_lshl_add_u64 v[238:239], s[70:71], 0, v[132:133]
	s_mov_b32 m0, s46
	v_lshl_add_u64 v[240:241], s[44:45], 0, v[130:131]
	global_load_lds_dwordx4 v[238:239], off
	v_lshl_add_u64 v[238:239], s[70:71], 0, v[128:129]
	s_mov_b32 m0, s47
	s_nop 0
	global_load_lds_dwordx4 v[238:239], off
	v_lshl_add_u64 v[238:239], s[44:45], 0, v[134:135]
	s_mov_b32 m0, s2
	s_nop 0
	global_load_lds_dwordx4 v[238:239], off
	s_mov_b32 m0, s48
	s_nop 0
	global_load_lds_dwordx4 v[240:241], off
	s_waitcnt vmcnt(16)
	s_cmp_lg_u32 s99, -1
	s_cbranch_scc1 .Lvmw_1607_1
	s_waitcnt vmcnt(8)
.Lvmw_1607_1:
	s_waitcnt lgkmcnt(0)
	s_barrier
	s_waitcnt lgkmcnt(0)
	v_mfma_f32_16x16x32_f16 v[60:63], v[172:175], v[204:207], 0
	v_mfma_f32_16x16x32_f16 v[56:59], v[180:183], v[204:207], 0
	v_mfma_f32_16x16x32_f16 v[44:47], v[172:175], v[212:215], 0
	v_mfma_f32_16x16x32_f16 v[40:43], v[180:183], v[212:215], 0
	v_mfma_f32_16x16x32_f16 v[28:31], v[172:175], v[220:223], 0
	v_mfma_f32_16x16x32_f16 v[24:27], v[180:183], v[220:223], 0
	v_mfma_f32_16x16x32_f16 v[12:15], v[172:175], v[228:231], 0
	v_mfma_f32_16x16x32_f16 v[8:11], v[180:183], v[228:231], 0
	v_mfma_f32_16x16x32_f16 v[60:63], v[176:179], v[208:211], v[60:63]
	v_mfma_f32_16x16x32_f16 v[56:59], v[184:187], v[208:211], v[56:59]
	v_mfma_f32_16x16x32_f16 v[44:47], v[176:179], v[216:219], v[44:47]
	v_mfma_f32_16x16x32_f16 v[40:43], v[184:187], v[216:219], v[40:43]
	v_mfma_f32_16x16x32_f16 v[28:31], v[176:179], v[224:227], v[28:31]
	v_mfma_f32_16x16x32_f16 v[24:27], v[184:187], v[224:227], v[24:27]
	v_mfma_f32_16x16x32_f16 v[12:15], v[176:179], v[232:235], v[12:15]
	v_mfma_f32_16x16x32_f16 v[8:11], v[184:187], v[232:235], v[8:11]
	v_mfma_f32_16x16x32_f16 v[52:55], v[188:191], v[204:207], 0
	v_mfma_f32_16x16x32_f16 v[48:51], v[196:199], v[204:207], 0
	v_mfma_f32_16x16x32_f16 v[36:39], v[188:191], v[212:215], 0
	v_mfma_f32_16x16x32_f16 v[32:35], v[196:199], v[212:215], 0
	v_mfma_f32_16x16x32_f16 v[20:23], v[188:191], v[220:223], 0
	v_mfma_f32_16x16x32_f16 v[16:19], v[196:199], v[220:223], 0
	v_mfma_f32_16x16x32_f16 v[4:7], v[188:191], v[228:231], 0
	v_mfma_f32_16x16x32_f16 v[0:3], v[196:199], v[228:231], 0
	v_mfma_f32_16x16x32_f16 v[52:55], v[192:195], v[208:211], v[52:55]
	v_mfma_f32_16x16x32_f16 v[48:51], v[200:203], v[208:211], v[48:51]
	v_mfma_f32_16x16x32_f16 v[36:39], v[192:195], v[216:219], v[36:39]
	v_mfma_f32_16x16x32_f16 v[32:35], v[200:203], v[216:219], v[32:35]
	v_mfma_f32_16x16x32_f16 v[20:23], v[192:195], v[224:227], v[20:23]
	v_mfma_f32_16x16x32_f16 v[16:19], v[200:203], v[224:227], v[16:19]
	v_mfma_f32_16x16x32_f16 v[4:7], v[192:195], v[232:235], v[4:7]
	v_mfma_f32_16x16x32_f16 v[0:3], v[200:203], v[232:235], v[0:3]
	s_barrier
; #define PG8_STAGE(bufoff, gbase, voff) do { _Pragma("unroll") for (int _i = 0; _i < 2; ++_i) \
;         __builtin_amdgcn_global_load_lds((const unsigned*)((const char*)(gbase) + (voff)[_i]), (PG8_LAS unsigned*)(lds + (bufoff) + ldsw + _i * 8192), 16, 0, 0); } while (0)
; #define PG8_LDA(dst, b, h) do { _Pragma("unroll") for (int m = 0; m < 4; ++m) _Pragma("unroll") for (int k = 0; k < 2; ++k) dst[m][k] = *(const PG8_LAS bf16x8*)(lds + PG8_SA(b, h) + aoff + m * 2048 + k * 1024); } while (0)
; #define PG8_LDB(dst, b, h) do { _Pragma("unroll") for (int n = 0; n < 2; ++n) _Pragma("unroll") for (int k = 0; k < 2; ++k) dst[n][k] = *(const PG8_LAS bf16x8*)(lds + PG8_SB(b, h) + boff + n * 2048 + k * 1024); } while (0)
; #define PG8_MMA(ai, bj, At, Bt) do { __builtin_amdgcn_s_setprio(1); _Pragma("unroll") for (int m = 0; m < 4; ++m) _Pragma("unroll") for (int n = 0; n < 2; ++n) _Pragma("unroll") for (int k = 0; k < 2; ++k) \
;         acc[ai][bj][m][n] = mma16<F16>(Bt[n][k], At[m][k], acc[ai][bj][m][n]); __builtin_amdgcn_s_setprio(0); } while (0)
; #define PG8_WAIT_V(n) asm volatile("s_waitcnt vmcnt(" #n ")" ::: "memory")
; #define PG8_WAIT_L(n) asm volatile("s_waitcnt lgkmcnt(" #n ")" ::: "memory")
; #define PG8_BAR __builtin_amdgcn_s_barrier()
; #define PG8_SCHED __builtin_amdgcn_sched_barrier(0)
; template <class Epi, class Sched, bool ALIGN_EPI = false, bool SP2 = false, bool F16 = false, bool TOKPERM = false>
; __device__ __forceinline__ void gemm_phase(PG8_LAS unsigned char* lds, const Gemm g, const Sched& S, const Epi& E, int wv) {
;     ...
;         for (int t = 0; t < nt; t += 2) {
;     ...
;             PG8_LDB(B0, 1, 0); PG8_LDB(B1, 1, 1); PG8_SCHED; PG8_LDA(At, 1, 0); PG8_STAGE(PG8_SA(0, 1), a2 + hstep, voffA);
;             PG8_WAIT_V(8); PG8_WAIT_L(0); PG8_BAR; PG8_MMA(0, 0, At, B0); PG8_MMA(0, 1, At, B1); PG8_BAR; PG8_SCHED;
;             PG8_LDA(At, 1, 1); PG8_STAGE(PG8_SB(1, 0), b3, voffB); PG8_STAGE(PG8_SB(1, 1), b3 + hstep, voffB); PG8_STAGE(PG8_SA(1, 0), a3, voffA);
;             PG8_WAIT_V(8); PG8_WAIT_L(0); PG8_BAR; PG8_MMA(1, 0, At, B0); PG8_MMA(1, 1, At, B1); PG8_BAR; PG8_SCHED;
	ds_read_b128 v[172:175], v163
	ds_read_b128 v[176:179], v164
	ds_read_b128 v[180:183], v165
	ds_read_b128 v[184:187], v166
	ds_read_b128 v[188:191], v167
	ds_read_b128 v[192:195], v168
	ds_read_b128 v[196:199], v169
	ds_read_b128 v[200:203], v170
	s_add_u32 s44, s44, 0x40000
	s_addc_u32 s45, s45, 0
	s_mov_b32 m0, s49
	v_lshl_add_u64 v[242:243], s[44:45], 0, v[134:135]
	ds_read_b128 v[204:207], v153 offset:32768
	ds_read_b128 v[208:211], v153 offset:33792
	ds_read_b128 v[212:215], v153 offset:34816
	ds_read_b128 v[216:219], v153 offset:35840
	ds_read_b128 v[220:223], v153 offset:36864
	ds_read_b128 v[224:227], v153 offset:37888
	ds_read_b128 v[228:231], v153 offset:38912
	ds_read_b128 v[232:235], v153 offset:39936
	global_load_lds_dwordx4 v[242:243], off
	v_lshl_add_u64 v[242:243], s[44:45], 0, v[130:131]
	s_mov_b32 m0, s50
	s_nop 0
	global_load_lds_dwordx4 v[242:243], off
	s_waitcnt vmcnt(8)
	s_waitcnt lgkmcnt(0)
	s_barrier
	s_waitcnt lgkmcnt(0)
	v_mfma_f32_16x16x32_f16 v[124:127], v[172:175], v[204:207], v[124:127]
	v_mfma_f32_16x16x32_f16 v[116:119], v[180:183], v[204:207], v[116:119]
	v_mfma_f32_16x16x32_f16 v[108:111], v[172:175], v[212:215], v[108:111]
	v_mfma_f32_16x16x32_f16 v[104:107], v[180:183], v[212:215], v[104:107]
	v_mfma_f32_16x16x32_f16 v[92:95], v[172:175], v[220:223], v[92:95]
	v_mfma_f32_16x16x32_f16 v[88:91], v[180:183], v[220:223], v[88:91]
	v_mfma_f32_16x16x32_f16 v[76:79], v[172:175], v[228:231], v[76:79]
	v_mfma_f32_16x16x32_f16 v[72:75], v[180:183], v[228:231], v[72:75]
	v_mfma_f32_16x16x32_f16 v[124:127], v[176:179], v[208:211], v[124:127]
	v_mfma_f32_16x16x32_f16 v[116:119], v[184:187], v[208:211], v[116:119]
	v_mfma_f32_16x16x32_f16 v[108:111], v[176:179], v[216:219], v[108:111]
	v_mfma_f32_16x16x32_f16 v[104:107], v[184:187], v[216:219], v[104:107]
	v_mfma_f32_16x16x32_f16 v[92:95], v[176:179], v[224:227], v[92:95]
	v_mfma_f32_16x16x32_f16 v[88:91], v[184:187], v[224:227], v[88:91]
	v_mfma_f32_16x16x32_f16 v[76:79], v[176:179], v[232:235], v[76:79]
	v_mfma_f32_16x16x32_f16 v[72:75], v[184:187], v[232:235], v[72:75]
	v_mfma_f32_16x16x32_f16 v[120:123], v[188:191], v[204:207], v[120:123]
	v_mfma_f32_16x16x32_f16 v[112:115], v[196:199], v[204:207], v[112:115]
	v_mfma_f32_16x16x32_f16 v[100:103], v[188:191], v[212:215], v[100:103]
	v_mfma_f32_16x16x32_f16 v[96:99], v[196:199], v[212:215], v[96:99]
	v_mfma_f32_16x16x32_f16 v[84:87], v[188:191], v[220:223], v[84:87]
	v_mfma_f32_16x16x32_f16 v[80:83], v[196:199], v[220:223], v[80:83]
	v_mfma_f32_16x16x32_f16 v[68:71], v[188:191], v[228:231], v[68:71]
	v_mfma_f32_16x16x32_f16 v[64:67], v[196:199], v[228:231], v[64:67]
	v_mfma_f32_16x16x32_f16 v[120:123], v[192:195], v[208:211], v[120:123]
	v_mfma_f32_16x16x32_f16 v[112:115], v[200:203], v[208:211], v[112:115]
	v_mfma_f32_16x16x32_f16 v[100:103], v[192:195], v[216:219], v[100:103]
	v_mfma_f32_16x16x32_f16 v[96:99], v[200:203], v[216:219], v[96:99]
	v_mfma_f32_16x16x32_f16 v[84:87], v[192:195], v[224:227], v[84:87]
	v_mfma_f32_16x16x32_f16 v[80:83], v[200:203], v[224:227], v[80:83]
	v_mfma_f32_16x16x32_f16 v[68:71], v[192:195], v[232:235], v[68:71]
	v_mfma_f32_16x16x32_f16 v[64:67], v[200:203], v[232:235], v[64:67]
	s_barrier
	s_mov_b32 m0, s52
	v_lshl_add_u64 v[148:149], v[148:149], 0, s[14:15]
	s_add_u32 s10, s10, 0x40080
	ds_read_b128 v[204:207], v153 offset:49152
	ds_read_b128 v[208:211], v153 offset:50176
	ds_read_b128 v[212:215], v153 offset:51200
	ds_read_b128 v[216:219], v153 offset:52224
	ds_read_b128 v[220:223], v153 offset:53248
	ds_read_b128 v[224:227], v153 offset:54272
	ds_read_b128 v[228:231], v153 offset:55296
	ds_read_b128 v[232:235], v153 offset:56320
	global_load_lds_dwordx4 v[148:149], off
	v_lshl_add_u64 v[148:149], v[236:237], 0, s[14:15]
	s_mov_b32 m0, s53
	s_addc_u32 s11, s11, 0
	global_load_lds_dwordx4 v[148:149], off
	v_lshl_add_u64 v[148:149], s[10:11], 0, v[132:133]
	s_mov_b32 m0, s56
	s_nop 0
	global_load_lds_dwordx4 v[148:149], off
	v_lshl_add_u64 v[148:149], s[10:11], 0, v[128:129]
	s_mov_b32 m0, s57
	s_nop 0
	global_load_lds_dwordx4 v[148:149], off
	v_lshl_add_u64 v[148:149], v[238:239], 0, s[14:15]
	s_mov_b32 m0, s54
	s_nop 0
	global_load_lds_dwordx4 v[148:149], off
	v_lshl_add_u64 v[148:149], v[240:241], 0, s[14:15]
	s_mov_b32 m0, s55
	s_nop 0
	global_load_lds_dwordx4 v[148:149], off
	s_waitcnt vmcnt(8)
	s_waitcnt lgkmcnt(0)
	s_barrier
	s_waitcnt lgkmcnt(0)
	v_mfma_f32_16x16x32_f16 v[60:63], v[172:175], v[204:207], v[60:63]
	v_mfma_f32_16x16x32_f16 v[56:59], v[180:183], v[204:207], v[56:59]
	v_mfma_f32_16x16x32_f16 v[44:47], v[172:175], v[212:215], v[44:47]
	v_mfma_f32_16x16x32_f16 v[40:43], v[180:183], v[212:215], v[40:43]
	v_mfma_f32_16x16x32_f16 v[28:31], v[172:175], v[220:223], v[28:31]
	v_mfma_f32_16x16x32_f16 v[24:27], v[180:183], v[220:223], v[24:27]
	v_mfma_f32_16x16x32_f16 v[12:15], v[172:175], v[228:231], v[12:15]
	v_mfma_f32_16x16x32_f16 v[8:11], v[180:183], v[228:231], v[8:11]
	v_mfma_f32_16x16x32_f16 v[60:63], v[176:179], v[208:211], v[60:63]
	v_mfma_f32_16x16x32_f16 v[56:59], v[184:187], v[208:211], v[56:59]
	v_mfma_f32_16x16x32_f16 v[44:47], v[176:179], v[216:219], v[44:47]
	v_mfma_f32_16x16x32_f16 v[40:43], v[184:187], v[216:219], v[40:43]
	v_mfma_f32_16x16x32_f16 v[28:31], v[176:179], v[224:227], v[28:31]
	v_mfma_f32_16x16x32_f16 v[24:27], v[184:187], v[224:227], v[24:27]
	v_mfma_f32_16x16x32_f16 v[12:15], v[176:179], v[232:235], v[12:15]
	v_mfma_f32_16x16x32_f16 v[8:11], v[184:187], v[232:235], v[8:11]
	v_mfma_f32_16x16x32_f16 v[52:55], v[188:191], v[204:207], v[52:55]
	v_mfma_f32_16x16x32_f16 v[48:51], v[196:199], v[204:207], v[48:51]
	v_mfma_f32_16x16x32_f16 v[36:39], v[188:191], v[212:215], v[36:39]
	v_mfma_f32_16x16x32_f16 v[32:35], v[196:199], v[212:215], v[32:35]
	v_mfma_f32_16x16x32_f16 v[20:23], v[188:191], v[220:223], v[20:23]
	v_mfma_f32_16x16x32_f16 v[16:19], v[196:199], v[220:223], v[16:19]
	v_mfma_f32_16x16x32_f16 v[4:7], v[188:191], v[228:231], v[4:7]
	v_mfma_f32_16x16x32_f16 v[0:3], v[196:199], v[228:231], v[0:3]
	v_mfma_f32_16x16x32_f16 v[52:55], v[192:195], v[208:211], v[52:55]
	v_mfma_f32_16x16x32_f16 v[48:51], v[200:203], v[208:211], v[48:51]
	v_mfma_f32_16x16x32_f16 v[36:39], v[192:195], v[216:219], v[36:39]
	v_mfma_f32_16x16x32_f16 v[32:35], v[200:203], v[216:219], v[32:35]
	v_mfma_f32_16x16x32_f16 v[20:23], v[192:195], v[224:227], v[20:23]
	v_mfma_f32_16x16x32_f16 v[16:19], v[200:203], v[224:227], v[16:19]
	v_mfma_f32_16x16x32_f16 v[4:7], v[192:195], v[232:235], v[4:7]
	v_mfma_f32_16x16x32_f16 v[0:3], v[200:203], v[232:235], v[0:3]
	s_barrier
	s_add_i32 s68, s68, 2
	s_add_u32 s8, s8, 0x100
	s_addc_u32 s9, s9, 0
	s_add_u32 s66, s66, 0x100
	s_addc_u32 s67, s67, 0
	s_cmp_gt_u32 s68, 13
